# P2 skinny path: meta-token f32 loads issued with the operand loads (one memory round trip less on 16 workgroups)
# speedup vs baseline: 1.0034x; 1.0034x over previous
; __global__ void __launch_bounds__(NT, 2) hymba_fwd(Args args) {
;     ...
;             const bf16* ap = ACT + (size_t)(MROW0 + fr) * DFF + wave * 352 + fq * 8;
;             const bf16* bp = W1O + (size_t)(64 * bid + fr) * DFF + wave * 352 + fq * 8;
;             bf16x8 av[11];
; #pragma unroll
;             for (int ks = 0; ks < 11; ++ks) av[ks] = *(const bf16x8*)(ap + ks * 32);
; #pragma unroll
;             for (int tp = 0; tp < 2; ++tp) { bf16x8 bv[2][11];
; #pragma unroll
;                 for (int t = 0; t < 2; ++t)
; #pragma unroll
;                     for (int ks = 0; ks < 11; ++ks) bv[t][ks] = *(const bf16x8*)(bp + (size_t)(2 * tp + t) * 16 * DFF + ks * 32);
; #pragma unroll
;                 for (int t = 0; t < 2; ++t)
; #pragma unroll
;                     for (int ks = 0; ks < 11; ++ks) acc[2 * tp + t] = __builtin_amdgcn_mfma_f32_16x16x32_bf16(av[ks], bv[t][ks], acc[2 * tp + t], 0, 0, 0); }
;     ...
;                 hv[e] = meta[(size_t)row * D + 64 * bid + c2 + e] + 0.5f * sm; sq += hv[e] * hv[e]; }
.LBB0_378:
.LBB0_379:
	v_and_b32_e32 v108, 15, v179
	s_waitcnt vmcnt(31)
	v_mul_u32_u24_e32 v0, 0xb00, v108
	v_readlane_b32 s18, v237, 6
	v_lshlrev_b32_e32 v0, 1, v0
	s_mov_b32 s5, 0
	s_waitcnt vmcnt(30)
	v_mov_b32_e32 v1, 0
	s_mul_i32 s4, s18, 0x160
	s_waitcnt vmcnt(28)
	v_lshl_add_u64 v[2:3], s[82:83], 0, v[0:1]
	s_lshl_b64 s[6:7], s[4:5], 1
	v_lshl_add_u64 v[2:3], v[2:3], 0, s[6:7]
	v_and_b32_e32 v0, 48, v178
	s_lshl_b32 s4, s68, 6
	s_waitcnt vmcnt(12)
	v_lshl_add_u64 v[18:19], v[2:3], 0, v[0:1]
	v_or_b32_e32 v4, s4, v108
	s_movk_i32 s5, 0x1600
	v_mov_b64_e32 v[2:3], s[12:13]
	v_mad_i64_i32 v[2:3], s[8:9], v4, s5, v[2:3]
	s_mov_b32 s5, 0x5800000
	v_add_co_u32_e32 v10, vcc, s5, v18
	v_lshl_add_u64 v[2:3], v[2:3], 0, s[6:7]
	s_nop 0
	v_addc_co_u32_e32 v11, vcc, 0, v19, vcc
	v_lshl_add_u64 v[78:79], v[2:3], 0, v[0:1]
	v_lshrrev_b32_e32 v110, 5, v179
	v_lshlrev_b32_e32 v110, 12, v110
	v_and_b32_e32 v111, 31, v179
	v_lshl_add_u32 v110, v111, 3, v110
	v_mov_b32_e32 v114, s4
	v_lshl_add_u32 v110, v114, 2, v110
	v_mov_b32_e32 v111, 0
	v_lshl_add_u64 v[112:113], s[14:15], 0, v[110:111]
	global_load_dwordx2 v[116:117], v[112:113], off
	global_load_dwordx4 v[2:5], v[10:11], off
	global_load_dwordx4 v[6:9], v[78:79], off
	s_mov_b32 s5, 0x16000
	v_add_co_u32_e32 v74, vcc, s5, v78
	s_mov_b32 s5, 0x2c000
	s_nop 0
	v_addc_co_u32_e32 v75, vcc, 0, v79, vcc
	global_load_dwordx4 v[10:13], v[74:75], off
	v_add_co_u32_e32 v76, vcc, s5, v78
	s_mov_b64 s[6:7], 0x5800000
	s_nop 0
	v_addc_co_u32_e32 v77, vcc, 0, v79, vcc
	v_lshl_add_u64 v[80:81], v[18:19], 0, s[6:7]
	global_load_dwordx4 v[14:17], v[76:77], off
	global_load_dwordx4 v[18:21], v[80:81], off offset:64
	global_load_dwordx4 v[22:25], v[78:79], off offset:64
	global_load_dwordx4 v[26:29], v[74:75], off offset:64
	global_load_dwordx4 v[30:33], v[76:77], off offset:64
	global_load_dwordx4 v[34:37], v[80:81], off offset:128
	global_load_dwordx4 v[38:41], v[78:79], off offset:128
	global_load_dwordx4 v[42:45], v[74:75], off offset:128
	global_load_dwordx4 v[46:49], v[76:77], off offset:128
	s_mov_b32 s5, 0x42000
	v_lshlrev_b32_e32 v0, 6, v178
	v_and_b32_e32 v0, 0xc00, v0
	s_movk_i32 s6, 0x7fff
	s_mov_b32 s7, 0xffff0000
	s_waitcnt vmcnt(10)
	v_mfma_f32_16x16x32_bf16 v[6:9], v[2:5], v[6:9], 0
	s_waitcnt vmcnt(9)
	v_mfma_f32_16x16x32_bf16 v[10:13], v[2:5], v[10:13], 0
	s_waitcnt vmcnt(6)
	v_mfma_f32_16x16x32_bf16 v[6:9], v[18:21], v[22:25], v[6:9]
	global_load_dwordx4 v[22:25], v[80:81], off offset:192
	s_waitcnt vmcnt(6)
	v_mfma_f32_16x16x32_bf16 v[10:13], v[18:21], v[26:29], v[10:13]
	global_load_dwordx4 v[26:29], v[78:79], off offset:192
	v_mfma_f32_16x16x32_bf16 v[14:17], v[2:5], v[14:17], 0
	s_waitcnt vmcnt(6)
	v_mfma_f32_16x16x32_bf16 v[14:17], v[18:21], v[30:33], v[14:17]
	global_load_dwordx4 v[30:33], v[74:75], off offset:192
	global_load_dwordx4 v[50:53], v[76:77], off offset:192
	s_waitcnt vmcnt(6)
	v_mfma_f32_16x16x32_bf16 v[6:9], v[34:37], v[38:41], v[6:9]
	global_load_dwordx4 v[38:41], v[80:81], off offset:256
	s_waitcnt vmcnt(6)
	v_mfma_f32_16x16x32_bf16 v[10:13], v[34:37], v[42:45], v[10:13]
	global_load_dwordx4 v[42:45], v[78:79], off offset:256
	s_waitcnt vmcnt(6)
	v_mfma_f32_16x16x32_bf16 v[14:17], v[34:37], v[46:49], v[14:17]
	global_load_dwordx4 v[46:49], v[74:75], off offset:256
	global_load_dwordx4 v[54:57], v[76:77], off offset:256
	s_waitcnt vmcnt(6)
	v_mfma_f32_16x16x32_bf16 v[6:9], v[22:25], v[26:29], v[6:9]
	global_load_dwordx4 v[26:29], v[80:81], off offset:320
	s_waitcnt vmcnt(6)
	v_mfma_f32_16x16x32_bf16 v[10:13], v[22:25], v[30:33], v[10:13]
	global_load_dwordx4 v[30:33], v[78:79], off offset:320
	s_waitcnt vmcnt(6)
	v_mfma_f32_16x16x32_bf16 v[14:17], v[22:25], v[50:53], v[14:17]
	global_load_dwordx4 v[50:53], v[74:75], off offset:320
	global_load_dwordx4 v[58:61], v[76:77], off offset:320
	s_waitcnt vmcnt(6)
	v_mfma_f32_16x16x32_bf16 v[6:9], v[38:41], v[42:45], v[6:9]
	global_load_dwordx4 v[42:45], v[80:81], off offset:384
	s_waitcnt vmcnt(6)
	v_mfma_f32_16x16x32_bf16 v[10:13], v[38:41], v[46:49], v[10:13]
	global_load_dwordx4 v[46:49], v[78:79], off offset:384
	s_waitcnt vmcnt(6)
	v_mfma_f32_16x16x32_bf16 v[14:17], v[38:41], v[54:57], v[14:17]
	global_load_dwordx4 v[54:57], v[74:75], off offset:384
	global_load_dwordx4 v[62:65], v[76:77], off offset:384
	s_waitcnt vmcnt(6)
	v_mfma_f32_16x16x32_bf16 v[6:9], v[26:29], v[30:33], v[6:9]
	global_load_dwordx4 v[30:33], v[80:81], off offset:448
	s_waitcnt vmcnt(6)
	v_mfma_f32_16x16x32_bf16 v[10:13], v[26:29], v[50:53], v[10:13]
	global_load_dwordx4 v[50:53], v[78:79], off offset:448
	s_waitcnt vmcnt(6)
	v_mfma_f32_16x16x32_bf16 v[14:17], v[26:29], v[58:61], v[14:17]
	global_load_dwordx4 v[58:61], v[74:75], off offset:448
	s_waitcnt vmcnt(5)
	v_mfma_f32_16x16x32_bf16 v[6:9], v[42:45], v[46:49], v[6:9]
	global_load_dwordx4 v[46:49], v[76:77], off offset:448
	s_waitcnt vmcnt(5)
	v_mfma_f32_16x16x32_bf16 v[10:13], v[42:45], v[54:57], v[10:13]
	global_load_dwordx4 v[54:57], v[80:81], off offset:512
	s_waitcnt vmcnt(5)
	v_mfma_f32_16x16x32_bf16 v[14:17], v[42:45], v[62:65], v[14:17]
	global_load_dwordx4 v[62:65], v[78:79], off offset:512
	s_waitcnt vmcnt(4)
	v_mfma_f32_16x16x32_bf16 v[6:9], v[30:33], v[50:53], v[6:9]
	global_load_dwordx4 v[50:53], v[74:75], off offset:512
	global_load_dwordx4 v[66:69], v[76:77], off offset:512
	s_waitcnt vmcnt(5)
	v_mfma_f32_16x16x32_bf16 v[10:13], v[30:33], v[58:61], v[10:13]
	global_load_dwordx4 v[58:61], v[80:81], off offset:576
	s_waitcnt vmcnt(5)
	v_mfma_f32_16x16x32_bf16 v[14:17], v[30:33], v[46:49], v[14:17]
	global_load_dwordx4 v[46:49], v[78:79], off offset:576
	s_waitcnt vmcnt(4)
; #define LAS __attribute__((address_space(3)))
; __device__ __forceinline__ unsigned pk2(float lo, float hi) { return f2bf(lo) | (f2bf(hi) << 16); }
; __global__ void __launch_bounds__(NT, 2) hymba_fwd(Args args) {
;     ...
;             for (int tp = 0; tp < 2; ++tp) { bf16x8 bv[2][11];
; #pragma unroll
;                 for (int t = 0; t < 2; ++t)
; #pragma unroll
;                     for (int ks = 0; ks < 11; ++ks) bv[t][ks] = *(const bf16x8*)(bp + (size_t)(2 * tp + t) * 16 * DFF + ks * 32);
; #pragma unroll
;                 for (int t = 0; t < 2; ++t)
; #pragma unroll
;                     for (int ks = 0; ks < 11; ++ks) acc[2 * tp + t] = __builtin_amdgcn_mfma_f32_16x16x32_bf16(av[ks], bv[t][ks], acc[2 * tp + t], 0, 0, 0); }
;             LAS float* part = (LAS float*)(lds + wave * 4096);
; #pragma unroll
;             for (int t = 0; t < 4; ++t)
; #pragma unroll
;                 for (int j = 0; j < 4; ++j) part[(fq * 4 + j) * 64 + t * 16 + fr] = acc[t][j];
;             __syncthreads();
;             const int row = tid >> 5, c2 = (tid & 31) * 2; float hv[2]; float sq = 0.f;
; #pragma unroll
;             for (int e = 0; e < 2; ++e) { float sm = 0.f;
; #pragma unroll
;                 for (int w = 0; w < 8; ++w) sm += ((LAS float*)(lds + w * 4096))[row * 64 + c2 + e];
;                 hv[e] = meta[(size_t)row * D + 64 * bid + c2 + e] + 0.5f * sm; sq += hv[e] * hv[e]; }
;             *(unsigned*)(ABUF + (size_t)(MROW0 + row) * D + 64 * bid + c2) = pk2(hv[0], hv[1]);
; #pragma unroll
;             for (int of = 1; of < 32; of <<= 1) sq += __shfl_xor(sq, of);
;             if ((tid & 31) == 0) SSQ1[(size_t)(MROW0 + row) * 16 + bid] = sq;
	v_mfma_f32_16x16x32_bf16 v[6:9], v[54:57], v[62:65], v[6:9]
	global_load_dwordx4 v[62:65], v[74:75], off offset:576
	global_load_dwordx4 v[70:73], v[76:77], off offset:576
	s_waitcnt vmcnt(5)
	v_mfma_f32_16x16x32_bf16 v[10:13], v[54:57], v[50:53], v[10:13]
	global_load_dwordx4 v[50:53], v[80:81], off offset:640
	s_waitcnt vmcnt(5)
	v_mfma_f32_16x16x32_bf16 v[14:17], v[54:57], v[66:69], v[14:17]
	global_load_dwordx4 v[66:69], v[78:79], off offset:640
	v_add_co_u32_e32 v78, vcc, s5, v78
	s_waitcnt vmcnt(4)
	v_mfma_f32_16x16x32_bf16 v[6:9], v[58:61], v[46:49], v[6:9]
	global_load_dwordx4 v[46:49], v[74:75], off offset:640
	v_addc_co_u32_e32 v79, vcc, 0, v79, vcc
	s_waitcnt vmcnt(4)
	v_mfma_f32_16x16x32_bf16 v[10:13], v[58:61], v[62:65], v[10:13]
	global_load_dwordx4 v[62:65], v[78:79], off
	s_lshl_b32 s5, s18, 12
	global_load_dwordx4 v[74:77], v[76:77], off offset:640
	s_waitcnt vmcnt(5)
	v_mfma_f32_16x16x32_bf16 v[14:17], v[58:61], v[70:73], v[14:17]
	s_add_i32 s5, s5, 0
	global_load_dwordx4 v[70:73], v[78:79], off offset:192
	s_waitcnt vmcnt(4)
	v_mfma_f32_16x16x32_bf16 v[6:9], v[50:53], v[66:69], v[6:9]
	global_load_dwordx4 v[66:69], v[78:79], off offset:64
	s_waitcnt vmcnt(4)
	v_mfma_f32_16x16x32_bf16 v[10:13], v[50:53], v[46:49], v[10:13]
	global_load_dwordx4 v[46:49], v[78:79], off offset:128
	s_waitcnt vmcnt(4)
	v_mfma_f32_16x16x32_bf16 v[2:5], v[2:5], v[62:65], 0
	global_load_dwordx4 v[62:65], v[78:79], off offset:256
	s_waitcnt vmcnt(4)
	v_mfma_f32_16x16x32_bf16 v[14:17], v[50:53], v[74:77], v[14:17]
	s_waitcnt vmcnt(2)
	v_mfma_f32_16x16x32_bf16 v[2:5], v[18:21], v[66:69], v[2:5]
	global_load_dwordx4 v[18:21], v[78:79], off offset:320
	s_waitcnt vmcnt(2)
	v_mfma_f32_16x16x32_bf16 v[2:5], v[34:37], v[46:49], v[2:5]
	global_load_dwordx4 v[34:37], v[78:79], off offset:384
	v_mfma_f32_16x16x32_bf16 v[2:5], v[22:25], v[70:73], v[2:5]
	global_load_dwordx4 v[22:25], v[78:79], off offset:448
	s_waitcnt vmcnt(3)
	v_mfma_f32_16x16x32_bf16 v[2:5], v[38:41], v[62:65], v[2:5]
	global_load_dwordx4 v[38:41], v[78:79], off offset:512
	s_waitcnt vmcnt(3)
	v_mfma_f32_16x16x32_bf16 v[2:5], v[26:29], v[18:21], v[2:5]
	global_load_dwordx4 v[18:21], v[78:79], off offset:576
	global_load_dwordx4 v[26:29], v[78:79], off offset:640
	s_waitcnt vmcnt(4)
	v_mfma_f32_16x16x32_bf16 v[2:5], v[42:45], v[34:37], v[2:5]
	s_waitcnt vmcnt(3)
	v_mfma_f32_16x16x32_bf16 v[2:5], v[30:33], v[22:25], v[2:5]
	v_lshlrev_b32_e32 v22, 2, v108
	v_add3_u32 v0, s5, v0, v22
	ds_write2_b32 v0, v6, v10 offset1:16
	s_waitcnt vmcnt(2)
	v_mfma_f32_16x16x32_bf16 v[2:5], v[54:57], v[38:41], v[2:5]
	ds_write2_b32 v0, v7, v11 offset0:64 offset1:80
	ds_write2_b32 v0, v8, v12 offset0:128 offset1:144
	ds_write2_b32 v0, v9, v13 offset0:192 offset1:208
	v_and_b32_e32 v22, 31, v179
	s_ashr_i32 s5, s4, 31
	v_mov_b32_e32 v23, 1
	s_waitcnt vmcnt(1)
	v_mfma_f32_16x16x32_bf16 v[2:5], v[58:61], v[18:21], v[2:5]
	s_waitcnt vmcnt(0)
	v_mfma_f32_16x16x32_bf16 v[2:5], v[50:53], v[26:29], v[2:5]
	s_nop 7
	ds_write2_b32 v0, v14, v2 offset0:32 offset1:48
	ds_write2_b32 v0, v15, v3 offset0:96 offset1:112
	ds_write2_b32 v0, v16, v4 offset0:160 offset1:176
	ds_write2_b32 v0, v17, v5 offset0:224 offset1:240
	v_lshrrev_b32_e32 v2, 5, v179
	v_lshlrev_b32_e32 v0, 12, v2
	v_lshl_add_u64 v[6:7], s[14:15], 0, v[0:1]
	v_lshlrev_b32_e32 v4, 3, v22
	v_lshl_add_u64 v[6:7], s[4:5], 2, v[6:7]
	v_mov_b32_e32 v5, v1
	v_lshl_add_u64 v[6:7], v[6:7], 0, v[4:5]
	s_waitcnt lgkmcnt(0)
	s_barrier
	s_waitcnt vmcnt(0)
	v_mov_b32_e32 v20, v116
	v_mov_b32_e32 v21, v117
	v_mbcnt_lo_u32_b32 v0, -1, 0
	v_lshlrev_b32_e32 v5, 8, v2
	v_mbcnt_hi_u32_b32 v0, -1, v0
	v_add3_u32 v16, 0, v5, v4
	v_and_b32_e32 v4, 64, v0
	v_xor_b32_e32 v5, 1, v0
	v_add_u32_e32 v27, 64, v4
	v_xor_b32_e32 v6, 2, v0
	v_cmp_lt_i32_e32 vcc, v5, v27
	v_xor_b32_e32 v24, 4, v0
	v_xor_b32_e32 v25, 8, v0
	v_cndmask_b32_e32 v8, v0, v5, vcc
	v_cmp_lt_i32_e32 vcc, v6, v27
	v_lshlrev_b32_e32 v29, 2, v8
	v_xor_b32_e32 v26, 16, v0
	v_cndmask_b32_e32 v28, v0, v6, vcc
	ds_read2st64_b64 v[4:7], v16 offset1:8
	ds_read2st64_b64 v[8:11], v16 offset0:16 offset1:24
	ds_read2st64_b64 v[12:15], v16 offset0:32 offset1:40
	ds_read2st64_b64 v[16:19], v16 offset0:48 offset1:56
	v_cmp_lt_i32_e32 vcc, v24, v27
	v_or_b32_e32 v3, 0x4000, v2
	s_waitcnt lgkmcnt(3)
	v_pk_add_f32 v[4:5], v[4:5], 0 op_sel_hi:[1,0]
	s_nop 0
	v_pk_add_f32 v[4:5], v[4:5], v[6:7]
	s_waitcnt lgkmcnt(2)
	v_pk_add_f32 v[4:5], v[4:5], v[8:9]
	v_cndmask_b32_e32 v8, v0, v24, vcc
	v_pk_add_f32 v[4:5], v[4:5], v[10:11]
	v_lshlrev_b32_e32 v10, 2, v28
	s_waitcnt lgkmcnt(1)
	v_pk_add_f32 v[4:5], v[4:5], v[12:13]
	v_lshlrev_b32_e32 v8, 2, v8
	v_pk_add_f32 v[4:5], v[4:5], v[14:15]
	v_cmp_lt_i32_e32 vcc, v25, v27
	s_waitcnt lgkmcnt(0)
	v_pk_add_f32 v[4:5], v[4:5], v[16:17]
	s_nop 0
	v_pk_add_f32 v[4:5], v[4:5], v[18:19]
	v_cndmask_b32_e32 v9, v0, v25, vcc
	v_lshlrev_b32_e32 v9, 2, v9
	v_cmp_lt_i32_e32 vcc, v26, v27
	s_waitcnt vmcnt(0)
	v_pk_fma_f32 v[4:5], v[4:5], 0.5, v[20:21] op_sel_hi:[1,0,1]
	s_nop 0
	v_pk_mul_f32 v[6:7], v[4:5], v[4:5]
	v_and_b32_sdwa v12, v4, v23 dst_sel:DWORD dst_unused:UNUSED_PAD src0_sel:WORD_1 src1_sel:DWORD
	v_add_f32_e32 v6, v6, v7
	ds_bpermute_b32 v7, v29, v6
	v_add3_u32 v4, v4, v12, s6
	v_lshrrev_b32_e32 v4, 16, v4
	s_waitcnt lgkmcnt(0)
	v_add_f32_e32 v6, v6, v7
	ds_bpermute_b32 v7, v10, v6
	v_cndmask_b32_e32 v10, v0, v26, vcc
	v_lshlrev_b32_e32 v0, 11, v3
	v_cmp_eq_u32_e32 vcc, 0, v22
	s_waitcnt lgkmcnt(0)
	v_add_f32_e32 v11, v6, v7
	ds_bpermute_b32 v8, v8, v11
	v_lshl_add_u64 v[6:7], s[80:81], 0, v[0:1]
	v_and_b32_sdwa v0, v5, v23 dst_sel:DWORD dst_unused:UNUSED_PAD src0_sel:WORD_1 src1_sel:DWORD
	v_add3_u32 v0, v5, v0, s6
	v_lshl_add_u64 v[6:7], s[4:5], 1, v[6:7]
	s_waitcnt lgkmcnt(0)
	v_add_f32_e32 v8, v11, v8
	ds_bpermute_b32 v9, v9, v8
	v_and_or_b32 v11, v0, s7, v4
	v_lshlrev_b32_e32 v0, 2, v10
	s_waitcnt lgkmcnt(0)
	v_add_f32_e32 v4, v8, v9
	ds_bpermute_b32 v5, v0, v4
	v_lshlrev_b32_e32 v0, 2, v22
	v_lshl_add_u64 v[6:7], v[6:7], 0, v[0:1]
	global_store_dword v[6:7], v11, off
	s_and_saveexec_b64 s[4:5], vcc
	s_cbranch_execz .LBB0_381
	v_lshlrev_b32_e32 v0, 6, v3
	v_lshl_add_u64 v[0:1], s[10:11], 0, v[0:1]
	s_ashr_i32 s69, s68, 31
	s_waitcnt lgkmcnt(0)
	v_add_f32_e32 v4, v4, v5
	v_lshl_add_u64 v[0:1], s[68:69], 2, v[0:1]
	global_store_dword v[0:1], v4, off
